# V-transposed key order permuted within 16-key groups so each stick-breaking PV fragment is one 16-byte load (half the V load instructions)
# speedup vs baseline: 1.0063x; 1.0063x over previous
; __device__ __forceinline__ bf16_t f2bf(float f) { unsigned u = __builtin_bit_cast(unsigned, f); return (bf16_t)((u + 0x7fffu + ((u >> 16) & 1u)) >> 16); }
;     __device__ __forceinline__ void operator()(const Acc& acc, const Unit& u, int wr, int wc, int fr, int fq) const {
;     ...
;             } else if (pn < 6) {
; #pragma unroll
;                 for (int ai = 0; ai < 2; ++ai)
; #pragma unroll
;                     for (int m = 0; m < 4; ++m) {
;                         const int row = u.pm * 256 + ai * 128 + wr * 64 + m * 16 + fr;
;                         const float rs = rsv[ai][m];
;                         const int b = row >> 13, t = row & (SEQ - 1);
; #pragma unroll
;                         for (int bj = 0; bj < 2; ++bj) {
;                             const int h = 4 * (pn - 4) + 2 * bj + (wc >> 1);
; #pragma unroll
;                             for (int n = 0; n < 2; ++n)
; #pragma unroll
;                                 for (int j = 0; j < 4; ++j) {
;                                     const int d = 32 * (wc & 1) + 8 * fq + 4 * n + j;
;                                     Vt[((size_t)(b * 8 + h) * 64 + d) * SEQ + t] = f2bf(acc[ai][bj][m][n][j] * rs);
;                                 }
;                         }
;                     }
.LBB0_204:
	s_andn2_b64 vcc, exec, s[0:1]
	s_cbranch_vccnz .LBB0_206
	v_and_b32_e32 v250, 4, v137
	v_and_b32_e32 v251, 8, v137
	v_lshlrev_b32_e32 v250, 1, v250
	v_lshrrev_b32_e32 v251, 1, v251
	v_or_b32_e32 v250, v250, v251
	v_and_b32_e32 v251, 0xfffffff3, v137
	v_or_b32_e32 v250, v250, v251
	s_add_u32 s0, s30, 0x8000000
	s_addc_u32 s1, s31, 0
	s_lshl_b32 s36, s60, 2
	v_readlane_b32 s37, v215, 43
	s_add_i32 s36, s36, s37
	s_and_b32 s37, s34, 0x1fc0
	v_or_b32_e32 v156, s37, v250
	s_ashr_i32 s37, s34, 10
	s_and_b32 s37, s37, -8
	s_add_i32 s38, s37, s36
	v_lshlrev_b32_e32 v156, 1, v156
	s_ashr_i32 s39, s38, 31
	v_lshl_add_u64 v[186:187], s[0:1], 0, v[156:157]
	s_lshl_b64 s[40:41], s[38:39], 19
	v_mul_f32_e32 v156, v120, v184
	v_bfe_u32 v158, v156, 16, 1
	v_mov_b32_e32 v189, s41
	v_or_b32_e32 v188, s40, v140
	v_add3_u32 v156, v156, v158, s52
	v_lshl_add_u64 v[188:189], v[188:189], 1, v[186:187]
	global_store_short_d16_hi v[188:189], v156, off
	v_mul_f32_e32 v156, v121, v184
	v_mov_b32_e32 v191, s41
	v_or_b32_e32 v190, s40, v142
	v_bfe_u32 v158, v156, 16, 1
	v_lshlrev_b64 v[190:191], 1, v[190:191]
	v_add3_u32 v156, v156, v158, s52
	v_lshl_add_u64 v[192:193], v[186:187], 0, v[190:191]
	global_store_short_d16_hi v[192:193], v156, off
	v_mul_f32_e32 v156, v122, v184
	v_mov_b32_e32 v193, s41
	v_or_b32_e32 v192, s40, v144
	v_bfe_u32 v158, v156, 16, 1
	v_lshlrev_b64 v[192:193], 1, v[192:193]
	v_add3_u32 v156, v156, v158, s52
	v_lshl_add_u64 v[194:195], v[186:187], 0, v[192:193]
	global_store_short_d16_hi v[194:195], v156, off
	v_mul_f32_e32 v156, v123, v184
	v_mov_b32_e32 v195, s41
	v_or_b32_e32 v194, s40, v146
	v_bfe_u32 v158, v156, 16, 1
	v_lshlrev_b64 v[194:195], 1, v[194:195]
	v_add3_u32 v156, v156, v158, s52
	v_lshl_add_u64 v[196:197], v[186:187], 0, v[194:195]
	global_store_short_d16_hi v[196:197], v156, off
	v_mul_f32_e32 v156, v124, v184
	v_mov_b32_e32 v197, s41
	v_or_b32_e32 v196, s40, v148
	v_bfe_u32 v158, v156, 16, 1
	v_lshlrev_b64 v[196:197], 1, v[196:197]
	v_add3_u32 v156, v156, v158, s52
	v_lshl_add_u64 v[198:199], v[186:187], 0, v[196:197]
	global_store_short_d16_hi v[198:199], v156, off
	v_mul_f32_e32 v156, v125, v184
	v_mov_b32_e32 v199, s41
	v_or_b32_e32 v198, s40, v150
	v_bfe_u32 v158, v156, 16, 1
	v_lshlrev_b64 v[198:199], 1, v[198:199]
	v_add3_u32 v156, v156, v158, s52
	v_lshl_add_u64 v[200:201], v[186:187], 0, v[198:199]
	global_store_short_d16_hi v[200:201], v156, off
	v_mul_f32_e32 v156, v126, v184
	v_mov_b32_e32 v201, s41
	v_or_b32_e32 v200, s40, v152
	v_bfe_u32 v158, v156, 16, 1
	v_lshlrev_b64 v[200:201], 1, v[200:201]
	v_add3_u32 v156, v156, v158, s52
	v_lshl_add_u64 v[202:203], v[186:187], 0, v[200:201]
	global_store_short_d16_hi v[202:203], v156, off
	v_mul_f32_e32 v156, v127, v184
	v_mov_b32_e32 v203, s41
	v_or_b32_e32 v202, s40, v154
	v_bfe_u32 v158, v156, 16, 1
	v_lshlrev_b64 v[202:203], 1, v[202:203]
	s_or_b32 s38, s38, 2
	v_add3_u32 v156, v156, v158, s52
	v_lshl_add_u64 v[204:205], v[186:187], 0, v[202:203]
	s_ashr_i32 s39, s38, 31
	global_store_short_d16_hi v[204:205], v156, off
	s_lshl_b64 s[38:39], s[38:39], 19
	v_mul_f32_e32 v156, v116, v184
	v_bfe_u32 v158, v156, 16, 1
	v_mov_b32_e32 v205, s39
	v_or_b32_e32 v204, s38, v140
	v_add3_u32 v156, v156, v158, s52
	v_lshl_add_u64 v[204:205], v[204:205], 1, v[186:187]
	global_store_short_d16_hi v[204:205], v156, off
	v_mul_f32_e32 v156, v117, v184
	v_mov_b32_e32 v207, s39
	v_or_b32_e32 v206, s38, v142
	v_bfe_u32 v158, v156, 16, 1
	v_lshlrev_b64 v[206:207], 1, v[206:207]
	v_add3_u32 v156, v156, v158, s52
	v_lshl_add_u64 v[208:209], v[186:187], 0, v[206:207]
	global_store_short_d16_hi v[208:209], v156, off
	v_mul_f32_e32 v156, v118, v184
	v_mov_b32_e32 v209, s39
	v_or_b32_e32 v208, s38, v144
	v_bfe_u32 v158, v156, 16, 1
	v_lshlrev_b64 v[208:209], 1, v[208:209]
	v_add3_u32 v156, v156, v158, s52
	v_lshl_add_u64 v[210:211], v[186:187], 0, v[208:209]
	global_store_short_d16_hi v[210:211], v156, off
	v_mul_f32_e32 v156, v119, v184
	v_mov_b32_e32 v211, s39
	v_or_b32_e32 v210, s38, v146
	v_bfe_u32 v158, v156, 16, 1
	v_lshlrev_b64 v[210:211], 1, v[210:211]
	v_add3_u32 v156, v156, v158, s52
	v_lshl_add_u64 v[216:217], v[186:187], 0, v[210:211]
	global_store_short_d16_hi v[216:217], v156, off
	v_mul_f32_e32 v156, v112, v184
	v_mov_b32_e32 v217, s39
	v_or_b32_e32 v216, s38, v148
	v_bfe_u32 v158, v156, 16, 1
	v_lshlrev_b64 v[216:217], 1, v[216:217]
	v_add3_u32 v156, v156, v158, s52
	v_lshl_add_u64 v[218:219], v[186:187], 0, v[216:217]
	global_store_short_d16_hi v[218:219], v156, off
	v_mul_f32_e32 v156, v113, v184
	v_mov_b32_e32 v219, s39
	v_or_b32_e32 v218, s38, v150
	v_bfe_u32 v158, v156, 16, 1
	v_lshlrev_b64 v[218:219], 1, v[218:219]
	v_add3_u32 v156, v156, v158, s52
	v_lshl_add_u64 v[220:221], v[186:187], 0, v[218:219]
	global_store_short_d16_hi v[220:221], v156, off
	v_mul_f32_e32 v156, v114, v184
	v_mov_b32_e32 v221, s39
	v_or_b32_e32 v220, s38, v152
	v_bfe_u32 v158, v156, 16, 1
	v_lshlrev_b64 v[220:221], 1, v[220:221]
	v_add3_u32 v156, v156, v158, s52
	v_lshl_add_u64 v[222:223], v[186:187], 0, v[220:221]
	global_store_short_d16_hi v[222:223], v156, off
	v_mul_f32_e32 v156, v115, v184
	v_mov_b32_e32 v223, s39
	v_or_b32_e32 v222, s38, v154
	v_bfe_u32 v158, v156, 16, 1
	v_lshlrev_b64 v[222:223], 1, v[222:223]
	v_add3_u32 v156, v156, v158, s52
	v_lshl_add_u64 v[224:225], v[186:187], 0, v[222:223]
	global_store_short_d16_hi v[224:225], v156, off
	v_mul_f32_e32 v156, v108, v182
	v_bfe_u32 v158, v156, 16, 1
	v_add3_u32 v156, v156, v158, s52
	global_store_short_d16_hi v[188:189], v156, off offset:32
	v_mul_f32_e32 v156, v109, v182
	v_lshl_add_u64 v[224:225], v[186:187], 0, 32
; __device__ __forceinline__ bf16_t f2bf(float f) { unsigned u = __builtin_bit_cast(unsigned, f); return (bf16_t)((u + 0x7fffu + ((u >> 16) & 1u)) >> 16); }
;     __device__ __forceinline__ void operator()(const Acc& acc, const Unit& u, int wr, int wc, int fr, int fq) const {
;     ...
;                         const int b = row >> 13, t = row & (SEQ - 1);
; #pragma unroll
;                         for (int bj = 0; bj < 2; ++bj) {
;                             const int h = 4 * (pn - 4) + 2 * bj + (wc >> 1);
; #pragma unroll
;                             for (int n = 0; n < 2; ++n)
; #pragma unroll
;                                 for (int j = 0; j < 4; ++j) {
;                                     const int d = 32 * (wc & 1) + 8 * fq + 4 * n + j;
;                                     Vt[((size_t)(b * 8 + h) * 64 + d) * SEQ + t] = f2bf(acc[ai][bj][m][n][j] * rs);
;                                 }
	v_bfe_u32 v158, v156, 16, 1
	v_add3_u32 v156, v156, v158, s52
	v_lshl_add_u64 v[226:227], v[224:225], 0, v[190:191]
	global_store_short_d16_hi v[226:227], v156, off
	v_mul_f32_e32 v156, v110, v182
	v_bfe_u32 v158, v156, 16, 1
	v_add3_u32 v156, v156, v158, s52
	v_lshl_add_u64 v[226:227], v[224:225], 0, v[192:193]
	global_store_short_d16_hi v[226:227], v156, off
	v_mul_f32_e32 v156, v111, v182
	v_bfe_u32 v158, v156, 16, 1
	v_add3_u32 v156, v156, v158, s52
	v_lshl_add_u64 v[226:227], v[224:225], 0, v[194:195]
	global_store_short_d16_hi v[226:227], v156, off
	v_mul_f32_e32 v156, v104, v182
	v_bfe_u32 v158, v156, 16, 1
	v_add3_u32 v156, v156, v158, s52
	v_lshl_add_u64 v[226:227], v[224:225], 0, v[196:197]
	global_store_short_d16_hi v[226:227], v156, off
	v_mul_f32_e32 v156, v105, v182
	v_bfe_u32 v158, v156, 16, 1
	v_add3_u32 v156, v156, v158, s52
	v_lshl_add_u64 v[226:227], v[224:225], 0, v[198:199]
	global_store_short_d16_hi v[226:227], v156, off
	v_mul_f32_e32 v156, v106, v182
	v_bfe_u32 v158, v156, 16, 1
	v_add3_u32 v156, v156, v158, s52
	v_lshl_add_u64 v[226:227], v[224:225], 0, v[200:201]
	global_store_short_d16_hi v[226:227], v156, off
	v_mul_f32_e32 v156, v107, v182
	v_bfe_u32 v158, v156, 16, 1
	v_add3_u32 v156, v156, v158, s52
	v_lshl_add_u64 v[226:227], v[224:225], 0, v[202:203]
	global_store_short_d16_hi v[226:227], v156, off
	v_mul_f32_e32 v156, v100, v182
	v_bfe_u32 v158, v156, 16, 1
	v_add3_u32 v156, v156, v158, s52
	global_store_short_d16_hi v[204:205], v156, off offset:32
	v_mul_f32_e32 v156, v101, v182
	v_bfe_u32 v158, v156, 16, 1
	v_add3_u32 v156, v156, v158, s52
	v_lshl_add_u64 v[226:227], v[224:225], 0, v[206:207]
	global_store_short_d16_hi v[226:227], v156, off
	v_mul_f32_e32 v156, v102, v182
	v_bfe_u32 v158, v156, 16, 1
	v_add3_u32 v156, v156, v158, s52
	v_lshl_add_u64 v[226:227], v[224:225], 0, v[208:209]
	global_store_short_d16_hi v[226:227], v156, off
	v_mul_f32_e32 v156, v103, v182
	v_bfe_u32 v158, v156, 16, 1
	v_add3_u32 v156, v156, v158, s52
	v_lshl_add_u64 v[226:227], v[224:225], 0, v[210:211]
	global_store_short_d16_hi v[226:227], v156, off
	v_mul_f32_e32 v156, v96, v182
	v_bfe_u32 v158, v156, 16, 1
	v_add3_u32 v156, v156, v158, s52
	v_lshl_add_u64 v[226:227], v[224:225], 0, v[216:217]
	global_store_short_d16_hi v[226:227], v156, off
	v_mul_f32_e32 v156, v97, v182
	v_bfe_u32 v158, v156, 16, 1
	v_add3_u32 v156, v156, v158, s52
	v_lshl_add_u64 v[226:227], v[224:225], 0, v[218:219]
	global_store_short_d16_hi v[226:227], v156, off
	v_mul_f32_e32 v156, v98, v182
	v_bfe_u32 v158, v156, 16, 1
	v_add3_u32 v156, v156, v158, s52
	v_lshl_add_u64 v[226:227], v[224:225], 0, v[220:221]
	global_store_short_d16_hi v[226:227], v156, off
	v_mul_f32_e32 v156, v99, v182
	v_bfe_u32 v158, v156, 16, 1
	v_add3_u32 v156, v156, v158, s52
	v_lshl_add_u64 v[224:225], v[224:225], 0, v[222:223]
	global_store_short_d16_hi v[224:225], v156, off
	v_mul_f32_e32 v156, v92, v180
	v_bfe_u32 v158, v156, 16, 1
	v_add3_u32 v156, v156, v158, s52
	global_store_short_d16_hi v[188:189], v156, off offset:64
	v_mul_f32_e32 v156, v93, v180
	v_lshl_add_u64 v[224:225], v[186:187], 0, 64
	v_bfe_u32 v158, v156, 16, 1
	v_add3_u32 v156, v156, v158, s52
	v_lshl_add_u64 v[226:227], v[224:225], 0, v[190:191]
	global_store_short_d16_hi v[226:227], v156, off
	v_mul_f32_e32 v156, v94, v180
	v_bfe_u32 v158, v156, 16, 1
	v_add3_u32 v156, v156, v158, s52
	v_lshl_add_u64 v[226:227], v[224:225], 0, v[192:193]
	global_store_short_d16_hi v[226:227], v156, off
	v_mul_f32_e32 v156, v95, v180
	v_bfe_u32 v158, v156, 16, 1
	v_add3_u32 v156, v156, v158, s52
	v_lshl_add_u64 v[226:227], v[224:225], 0, v[194:195]
	global_store_short_d16_hi v[226:227], v156, off
	v_mul_f32_e32 v156, v88, v180
	v_bfe_u32 v158, v156, 16, 1
	v_add3_u32 v156, v156, v158, s52
	v_lshl_add_u64 v[226:227], v[224:225], 0, v[196:197]
	global_store_short_d16_hi v[226:227], v156, off
	v_mul_f32_e32 v156, v89, v180
	v_bfe_u32 v158, v156, 16, 1
	v_add3_u32 v156, v156, v158, s52
	v_lshl_add_u64 v[226:227], v[224:225], 0, v[198:199]
	global_store_short_d16_hi v[226:227], v156, off
	v_mul_f32_e32 v156, v90, v180
	v_bfe_u32 v158, v156, 16, 1
	v_add3_u32 v156, v156, v158, s52
	v_lshl_add_u64 v[226:227], v[224:225], 0, v[200:201]
	global_store_short_d16_hi v[226:227], v156, off
	v_mul_f32_e32 v156, v91, v180
	v_bfe_u32 v158, v156, 16, 1
	v_add3_u32 v156, v156, v158, s52
	v_lshl_add_u64 v[226:227], v[224:225], 0, v[202:203]
	global_store_short_d16_hi v[226:227], v156, off
	v_mul_f32_e32 v156, v84, v180
	v_bfe_u32 v158, v156, 16, 1
	v_add3_u32 v156, v156, v158, s52
	global_store_short_d16_hi v[204:205], v156, off offset:64
	v_mul_f32_e32 v156, v85, v180
	v_bfe_u32 v158, v156, 16, 1
	v_add3_u32 v156, v156, v158, s52
	v_lshl_add_u64 v[226:227], v[224:225], 0, v[206:207]
	global_store_short_d16_hi v[226:227], v156, off
	v_mul_f32_e32 v156, v86, v180
	v_bfe_u32 v158, v156, 16, 1
	v_add3_u32 v156, v156, v158, s52
	v_lshl_add_u64 v[226:227], v[224:225], 0, v[208:209]
	global_store_short_d16_hi v[226:227], v156, off
	v_mul_f32_e32 v156, v87, v180
	v_bfe_u32 v158, v156, 16, 1
	v_add3_u32 v156, v156, v158, s52
	v_lshl_add_u64 v[226:227], v[224:225], 0, v[210:211]
	global_store_short_d16_hi v[226:227], v156, off
	v_mul_f32_e32 v156, v80, v180
	v_bfe_u32 v158, v156, 16, 1
	v_add3_u32 v156, v156, v158, s52
	v_lshl_add_u64 v[226:227], v[224:225], 0, v[216:217]
	global_store_short_d16_hi v[226:227], v156, off
	v_mul_f32_e32 v156, v81, v180
	v_bfe_u32 v158, v156, 16, 1
	v_add3_u32 v156, v156, v158, s52
	v_lshl_add_u64 v[226:227], v[224:225], 0, v[218:219]
	global_store_short_d16_hi v[226:227], v156, off
	v_mul_f32_e32 v156, v82, v180
; __device__ __forceinline__ bf16_t f2bf(float f) { unsigned u = __builtin_bit_cast(unsigned, f); return (bf16_t)((u + 0x7fffu + ((u >> 16) & 1u)) >> 16); }
;     __device__ __forceinline__ void operator()(const Acc& acc, const Unit& u, int wr, int wc, int fr, int fq) const {
;     ...
;                         const int b = row >> 13, t = row & (SEQ - 1);
; #pragma unroll
;                         for (int bj = 0; bj < 2; ++bj) {
;                             const int h = 4 * (pn - 4) + 2 * bj + (wc >> 1);
; #pragma unroll
;                             for (int n = 0; n < 2; ++n)
; #pragma unroll
;                                 for (int j = 0; j < 4; ++j) {
;                                     const int d = 32 * (wc & 1) + 8 * fq + 4 * n + j;
;                                     Vt[((size_t)(b * 8 + h) * 64 + d) * SEQ + t] = f2bf(acc[ai][bj][m][n][j] * rs);
;                                 }
	v_bfe_u32 v158, v156, 16, 1
	v_add3_u32 v156, v156, v158, s52
	v_lshl_add_u64 v[226:227], v[224:225], 0, v[220:221]
	global_store_short_d16_hi v[226:227], v156, off
	v_mul_f32_e32 v156, v83, v180
	v_bfe_u32 v158, v156, 16, 1
	v_add3_u32 v156, v156, v158, s52
	v_lshl_add_u64 v[224:225], v[224:225], 0, v[222:223]
	global_store_short_d16_hi v[224:225], v156, off
	v_mul_f32_e32 v156, v76, v178
	v_bfe_u32 v158, v156, 16, 1
	v_add3_u32 v156, v156, v158, s52
	s_mov_b64 s[38:39], 0x60
	global_store_short_d16_hi v[188:189], v156, off offset:96
	v_mul_f32_e32 v156, v77, v178
	v_lshl_add_u64 v[186:187], v[186:187], 0, s[38:39]
	v_bfe_u32 v158, v156, 16, 1
	v_add3_u32 v156, v156, v158, s52
	v_lshl_add_u64 v[188:189], v[186:187], 0, v[190:191]
	global_store_short_d16_hi v[188:189], v156, off
	v_mul_f32_e32 v156, v78, v178
	v_bfe_u32 v158, v156, 16, 1
	v_add3_u32 v156, v156, v158, s52
	v_lshl_add_u64 v[188:189], v[186:187], 0, v[192:193]
	global_store_short_d16_hi v[188:189], v156, off
	v_mul_f32_e32 v156, v79, v178
	v_bfe_u32 v158, v156, 16, 1
	v_add3_u32 v156, v156, v158, s52
	v_lshl_add_u64 v[188:189], v[186:187], 0, v[194:195]
	global_store_short_d16_hi v[188:189], v156, off
	v_mul_f32_e32 v156, v72, v178
	v_bfe_u32 v158, v156, 16, 1
	v_add3_u32 v156, v156, v158, s52
	v_lshl_add_u64 v[188:189], v[186:187], 0, v[196:197]
	global_store_short_d16_hi v[188:189], v156, off
	v_mul_f32_e32 v156, v73, v178
	v_bfe_u32 v158, v156, 16, 1
	v_add3_u32 v156, v156, v158, s52
	v_lshl_add_u64 v[188:189], v[186:187], 0, v[198:199]
	global_store_short_d16_hi v[188:189], v156, off
	v_mul_f32_e32 v156, v74, v178
	v_bfe_u32 v158, v156, 16, 1
	v_add3_u32 v156, v156, v158, s52
	v_lshl_add_u64 v[188:189], v[186:187], 0, v[200:201]
	global_store_short_d16_hi v[188:189], v156, off
	v_mul_f32_e32 v156, v75, v178
	v_bfe_u32 v158, v156, 16, 1
	v_add3_u32 v156, v156, v158, s52
	v_lshl_add_u64 v[188:189], v[186:187], 0, v[202:203]
	global_store_short_d16_hi v[188:189], v156, off
	v_mul_f32_e32 v156, v68, v178
	v_bfe_u32 v158, v156, 16, 1
	v_add3_u32 v156, v156, v158, s52
	global_store_short_d16_hi v[204:205], v156, off offset:96
	v_mul_f32_e32 v156, v69, v178
	v_bfe_u32 v158, v156, 16, 1
	v_add3_u32 v156, v156, v158, s52
	v_lshl_add_u64 v[188:189], v[186:187], 0, v[206:207]
	global_store_short_d16_hi v[188:189], v156, off
	v_mul_f32_e32 v156, v70, v178
	v_bfe_u32 v158, v156, 16, 1
	v_add3_u32 v156, v156, v158, s52
	v_lshl_add_u64 v[188:189], v[186:187], 0, v[208:209]
	global_store_short_d16_hi v[188:189], v156, off
	v_mul_f32_e32 v156, v71, v178
	v_bfe_u32 v158, v156, 16, 1
	v_add3_u32 v156, v156, v158, s52
	v_lshl_add_u64 v[188:189], v[186:187], 0, v[210:211]
	global_store_short_d16_hi v[188:189], v156, off
	v_mul_f32_e32 v156, v64, v178
	v_bfe_u32 v158, v156, 16, 1
	v_add3_u32 v156, v156, v158, s52
	v_lshl_add_u64 v[188:189], v[186:187], 0, v[216:217]
	global_store_short_d16_hi v[188:189], v156, off
	v_mul_f32_e32 v156, v65, v178
	v_bfe_u32 v158, v156, 16, 1
	v_add3_u32 v156, v156, v158, s52
	v_lshl_add_u64 v[188:189], v[186:187], 0, v[218:219]
	global_store_short_d16_hi v[188:189], v156, off
	v_mul_f32_e32 v156, v66, v178
	v_bfe_u32 v158, v156, 16, 1
	v_add3_u32 v156, v156, v158, s52
	v_lshl_add_u64 v[188:189], v[186:187], 0, v[220:221]
	global_store_short_d16_hi v[188:189], v156, off
	v_mul_f32_e32 v156, v67, v178
	s_addk_i32 s34, 0x80
	v_bfe_u32 v158, v156, 16, 1
	s_and_b32 s37, s34, 0x1fc0
	s_ashr_i32 s34, s34, 10
	v_add3_u32 v156, v156, v158, s52
	v_lshl_add_u64 v[186:187], v[186:187], 0, v[222:223]
	s_and_b32 s34, s34, -8
	global_store_short_d16_hi v[186:187], v156, off
	v_or_b32_e32 v156, s37, v250
	s_add_i32 s36, s34, s36
	v_lshlrev_b32_e32 v156, 1, v156
	s_ashr_i32 s37, s36, 31
	v_lshl_add_u64 v[186:187], s[0:1], 0, v[156:157]
	s_lshl_b64 s[0:1], s[36:37], 19
	v_mul_f32_e32 v156, v60, v176
	v_bfe_u32 v158, v156, 16, 1
	v_mov_b32_e32 v189, s1
	v_or_b32_e32 v188, s0, v140
	v_add3_u32 v156, v156, v158, s52
	v_lshl_add_u64 v[188:189], v[188:189], 1, v[186:187]
	global_store_short_d16_hi v[188:189], v156, off
	v_mul_f32_e32 v156, v61, v176
	v_mov_b32_e32 v191, s1
	v_or_b32_e32 v190, s0, v142
	v_bfe_u32 v158, v156, 16, 1
	v_lshlrev_b64 v[190:191], 1, v[190:191]
	v_add3_u32 v156, v156, v158, s52
	v_lshl_add_u64 v[192:193], v[186:187], 0, v[190:191]
	global_store_short_d16_hi v[192:193], v156, off
	v_mul_f32_e32 v156, v62, v176
	v_mov_b32_e32 v193, s1
	v_or_b32_e32 v192, s0, v144
	v_bfe_u32 v158, v156, 16, 1
	v_lshlrev_b64 v[192:193], 1, v[192:193]
	v_add3_u32 v156, v156, v158, s52
	v_lshl_add_u64 v[194:195], v[186:187], 0, v[192:193]
	global_store_short_d16_hi v[194:195], v156, off
	v_mul_f32_e32 v156, v63, v176
	v_mov_b32_e32 v195, s1
	v_or_b32_e32 v194, s0, v146
	v_bfe_u32 v158, v156, 16, 1
	v_lshlrev_b64 v[194:195], 1, v[194:195]
	v_add3_u32 v156, v156, v158, s52
	v_lshl_add_u64 v[196:197], v[186:187], 0, v[194:195]
	global_store_short_d16_hi v[196:197], v156, off
	v_mul_f32_e32 v156, v56, v176
	v_mov_b32_e32 v197, s1
	v_or_b32_e32 v196, s0, v148
	v_bfe_u32 v158, v156, 16, 1
	v_lshlrev_b64 v[196:197], 1, v[196:197]
	v_add3_u32 v156, v156, v158, s52
	v_lshl_add_u64 v[198:199], v[186:187], 0, v[196:197]
	global_store_short_d16_hi v[198:199], v156, off
	v_mul_f32_e32 v156, v57, v176
	v_mov_b32_e32 v199, s1
	v_or_b32_e32 v198, s0, v150
	v_bfe_u32 v158, v156, 16, 1
	v_lshlrev_b64 v[198:199], 1, v[198:199]
	v_add3_u32 v156, v156, v158, s52
	v_lshl_add_u64 v[200:201], v[186:187], 0, v[198:199]
	global_store_short_d16_hi v[200:201], v156, off
	v_mul_f32_e32 v156, v58, v176
	v_mov_b32_e32 v201, s1
	v_or_b32_e32 v200, s0, v152
	v_bfe_u32 v158, v156, 16, 1
	v_lshlrev_b64 v[200:201], 1, v[200:201]
; __device__ __forceinline__ bf16_t f2bf(float f) { unsigned u = __builtin_bit_cast(unsigned, f); return (bf16_t)((u + 0x7fffu + ((u >> 16) & 1u)) >> 16); }
;     __device__ __forceinline__ void operator()(const Acc& acc, const Unit& u, int wr, int wc, int fr, int fq) const {
;     ...
;                         const int b = row >> 13, t = row & (SEQ - 1);
; #pragma unroll
;                         for (int bj = 0; bj < 2; ++bj) {
;                             const int h = 4 * (pn - 4) + 2 * bj + (wc >> 1);
; #pragma unroll
;                             for (int n = 0; n < 2; ++n)
; #pragma unroll
;                                 for (int j = 0; j < 4; ++j) {
;                                     const int d = 32 * (wc & 1) + 8 * fq + 4 * n + j;
;                                     Vt[((size_t)(b * 8 + h) * 64 + d) * SEQ + t] = f2bf(acc[ai][bj][m][n][j] * rs);
;                                 }
	v_add3_u32 v156, v156, v158, s52
	v_lshl_add_u64 v[202:203], v[186:187], 0, v[200:201]
	global_store_short_d16_hi v[202:203], v156, off
	v_mul_f32_e32 v156, v59, v176
	v_mov_b32_e32 v203, s1
	v_or_b32_e32 v202, s0, v154
	v_bfe_u32 v158, v156, 16, 1
	v_lshlrev_b64 v[202:203], 1, v[202:203]
	s_or_b32 s0, s36, 2
	v_add3_u32 v156, v156, v158, s52
	v_lshl_add_u64 v[204:205], v[186:187], 0, v[202:203]
	s_ashr_i32 s1, s0, 31
	global_store_short_d16_hi v[204:205], v156, off
	s_lshl_b64 s[0:1], s[0:1], 19
	v_mul_f32_e32 v156, v52, v176
	v_bfe_u32 v158, v156, 16, 1
	v_mov_b32_e32 v205, s1
	v_or_b32_e32 v204, s0, v140
	v_add3_u32 v156, v156, v158, s52
	v_lshl_add_u64 v[204:205], v[204:205], 1, v[186:187]
	global_store_short_d16_hi v[204:205], v156, off
	v_mul_f32_e32 v156, v53, v176
	v_mov_b32_e32 v207, s1
	v_or_b32_e32 v206, s0, v142
	v_bfe_u32 v158, v156, 16, 1
	v_lshlrev_b64 v[206:207], 1, v[206:207]
	v_add3_u32 v156, v156, v158, s52
	v_lshl_add_u64 v[208:209], v[186:187], 0, v[206:207]
	global_store_short_d16_hi v[208:209], v156, off
	v_mul_f32_e32 v156, v54, v176
	v_mov_b32_e32 v209, s1
	v_or_b32_e32 v208, s0, v144
	v_bfe_u32 v158, v156, 16, 1
	v_lshlrev_b64 v[208:209], 1, v[208:209]
	v_add3_u32 v156, v156, v158, s52
	v_lshl_add_u64 v[210:211], v[186:187], 0, v[208:209]
	global_store_short_d16_hi v[210:211], v156, off
	v_mul_f32_e32 v156, v55, v176
	v_mov_b32_e32 v211, s1
	v_or_b32_e32 v210, s0, v146
	v_bfe_u32 v158, v156, 16, 1
	v_lshlrev_b64 v[210:211], 1, v[210:211]
	v_add3_u32 v156, v156, v158, s52
	v_lshl_add_u64 v[216:217], v[186:187], 0, v[210:211]
	global_store_short_d16_hi v[216:217], v156, off
	v_mul_f32_e32 v156, v48, v176
	v_mov_b32_e32 v217, s1
	v_or_b32_e32 v216, s0, v148
	v_bfe_u32 v158, v156, 16, 1
	v_lshlrev_b64 v[216:217], 1, v[216:217]
	v_add3_u32 v156, v156, v158, s52
	v_lshl_add_u64 v[218:219], v[186:187], 0, v[216:217]
	global_store_short_d16_hi v[218:219], v156, off
	v_mul_f32_e32 v156, v49, v176
	v_mov_b32_e32 v219, s1
	v_or_b32_e32 v218, s0, v150
	v_bfe_u32 v158, v156, 16, 1
	v_lshlrev_b64 v[218:219], 1, v[218:219]
	v_add3_u32 v156, v156, v158, s52
	v_lshl_add_u64 v[220:221], v[186:187], 0, v[218:219]
	global_store_short_d16_hi v[220:221], v156, off
	v_mul_f32_e32 v156, v50, v176
	v_mov_b32_e32 v221, s1
	v_or_b32_e32 v220, s0, v152
	v_bfe_u32 v158, v156, 16, 1
	v_lshlrev_b64 v[220:221], 1, v[220:221]
	v_add3_u32 v156, v156, v158, s52
	v_lshl_add_u64 v[222:223], v[186:187], 0, v[220:221]
	global_store_short_d16_hi v[222:223], v156, off
	v_mul_f32_e32 v156, v51, v176
	v_mov_b32_e32 v223, s1
	v_or_b32_e32 v222, s0, v154
	v_bfe_u32 v158, v156, 16, 1
	v_lshlrev_b64 v[222:223], 1, v[222:223]
	v_add3_u32 v156, v156, v158, s52
	v_lshl_add_u64 v[224:225], v[186:187], 0, v[222:223]
	global_store_short_d16_hi v[224:225], v156, off
	v_mul_f32_e32 v156, v44, v174
	v_bfe_u32 v158, v156, 16, 1
	v_add3_u32 v156, v156, v158, s52
	global_store_short_d16_hi v[188:189], v156, off offset:32
	v_mul_f32_e32 v156, v45, v174
	v_lshl_add_u64 v[224:225], v[186:187], 0, 32
	v_bfe_u32 v158, v156, 16, 1
	v_add3_u32 v156, v156, v158, s52
	v_lshl_add_u64 v[226:227], v[224:225], 0, v[190:191]
	global_store_short_d16_hi v[226:227], v156, off
	v_mul_f32_e32 v156, v46, v174
	v_bfe_u32 v158, v156, 16, 1
	v_add3_u32 v156, v156, v158, s52
	v_lshl_add_u64 v[226:227], v[224:225], 0, v[192:193]
	global_store_short_d16_hi v[226:227], v156, off
	v_mul_f32_e32 v156, v47, v174
	v_bfe_u32 v158, v156, 16, 1
	v_add3_u32 v156, v156, v158, s52
	v_lshl_add_u64 v[226:227], v[224:225], 0, v[194:195]
	global_store_short_d16_hi v[226:227], v156, off
	v_mul_f32_e32 v156, v40, v174
	v_bfe_u32 v158, v156, 16, 1
	v_add3_u32 v156, v156, v158, s52
	v_lshl_add_u64 v[226:227], v[224:225], 0, v[196:197]
	global_store_short_d16_hi v[226:227], v156, off
	v_mul_f32_e32 v156, v41, v174
	v_bfe_u32 v158, v156, 16, 1
	v_add3_u32 v156, v156, v158, s52
	v_lshl_add_u64 v[226:227], v[224:225], 0, v[198:199]
	global_store_short_d16_hi v[226:227], v156, off
	v_mul_f32_e32 v156, v42, v174
	v_bfe_u32 v158, v156, 16, 1
	v_add3_u32 v156, v156, v158, s52
	v_lshl_add_u64 v[226:227], v[224:225], 0, v[200:201]
	global_store_short_d16_hi v[226:227], v156, off
	v_mul_f32_e32 v156, v43, v174
	v_bfe_u32 v158, v156, 16, 1
	v_add3_u32 v156, v156, v158, s52
	v_lshl_add_u64 v[226:227], v[224:225], 0, v[202:203]
	global_store_short_d16_hi v[226:227], v156, off
	v_mul_f32_e32 v156, v36, v174
	v_bfe_u32 v158, v156, 16, 1
	v_add3_u32 v156, v156, v158, s52
	global_store_short_d16_hi v[204:205], v156, off offset:32
	v_mul_f32_e32 v156, v37, v174
	v_bfe_u32 v158, v156, 16, 1
	v_add3_u32 v156, v156, v158, s52
	v_lshl_add_u64 v[226:227], v[224:225], 0, v[206:207]
	global_store_short_d16_hi v[226:227], v156, off
	v_mul_f32_e32 v156, v38, v174
	v_bfe_u32 v158, v156, 16, 1
	v_add3_u32 v156, v156, v158, s52
	v_lshl_add_u64 v[226:227], v[224:225], 0, v[208:209]
	global_store_short_d16_hi v[226:227], v156, off
	v_mul_f32_e32 v156, v39, v174
	v_bfe_u32 v158, v156, 16, 1
	v_add3_u32 v156, v156, v158, s52
	v_lshl_add_u64 v[226:227], v[224:225], 0, v[210:211]
	global_store_short_d16_hi v[226:227], v156, off
	v_mul_f32_e32 v156, v32, v174
	v_bfe_u32 v158, v156, 16, 1
	v_add3_u32 v156, v156, v158, s52
	v_lshl_add_u64 v[226:227], v[224:225], 0, v[216:217]
	global_store_short_d16_hi v[226:227], v156, off
	v_mul_f32_e32 v156, v33, v174
	v_bfe_u32 v158, v156, 16, 1
	v_add3_u32 v156, v156, v158, s52
	v_lshl_add_u64 v[226:227], v[224:225], 0, v[218:219]
	global_store_short_d16_hi v[226:227], v156, off
	v_mul_f32_e32 v156, v34, v174
	v_bfe_u32 v158, v156, 16, 1
	v_add3_u32 v156, v156, v158, s52
	v_lshl_add_u64 v[226:227], v[224:225], 0, v[220:221]
; __device__ __forceinline__ bf16_t f2bf(float f) { unsigned u = __builtin_bit_cast(unsigned, f); return (bf16_t)((u + 0x7fffu + ((u >> 16) & 1u)) >> 16); }
;     __device__ __forceinline__ void operator()(const Acc& acc, const Unit& u, int wr, int wc, int fr, int fq) const {
;     ...
;                         const int b = row >> 13, t = row & (SEQ - 1);
; #pragma unroll
;                         for (int bj = 0; bj < 2; ++bj) {
;                             const int h = 4 * (pn - 4) + 2 * bj + (wc >> 1);
; #pragma unroll
;                             for (int n = 0; n < 2; ++n)
; #pragma unroll
;                                 for (int j = 0; j < 4; ++j) {
;                                     const int d = 32 * (wc & 1) + 8 * fq + 4 * n + j;
;                                     Vt[((size_t)(b * 8 + h) * 64 + d) * SEQ + t] = f2bf(acc[ai][bj][m][n][j] * rs);
;                                 }
	global_store_short_d16_hi v[226:227], v156, off
	v_mul_f32_e32 v156, v35, v174
	v_bfe_u32 v158, v156, 16, 1
	v_add3_u32 v156, v156, v158, s52
	v_lshl_add_u64 v[224:225], v[224:225], 0, v[222:223]
	global_store_short_d16_hi v[224:225], v156, off
	v_mul_f32_e32 v156, v28, v172
	v_bfe_u32 v158, v156, 16, 1
	v_add3_u32 v156, v156, v158, s52
	global_store_short_d16_hi v[188:189], v156, off offset:64
	v_mul_f32_e32 v156, v29, v172
	v_lshl_add_u64 v[224:225], v[186:187], 0, 64
	v_bfe_u32 v158, v156, 16, 1
	v_add3_u32 v156, v156, v158, s52
	v_lshl_add_u64 v[226:227], v[224:225], 0, v[190:191]
	global_store_short_d16_hi v[226:227], v156, off
	v_mul_f32_e32 v156, v30, v172
	v_bfe_u32 v158, v156, 16, 1
	v_add3_u32 v156, v156, v158, s52
	v_lshl_add_u64 v[226:227], v[224:225], 0, v[192:193]
	global_store_short_d16_hi v[226:227], v156, off
	v_mul_f32_e32 v156, v31, v172
	v_bfe_u32 v158, v156, 16, 1
	v_add3_u32 v156, v156, v158, s52
	v_lshl_add_u64 v[226:227], v[224:225], 0, v[194:195]
	global_store_short_d16_hi v[226:227], v156, off
	v_mul_f32_e32 v156, v24, v172
	v_bfe_u32 v158, v156, 16, 1
	v_add3_u32 v156, v156, v158, s52
	v_lshl_add_u64 v[226:227], v[224:225], 0, v[196:197]
	global_store_short_d16_hi v[226:227], v156, off
	v_mul_f32_e32 v156, v25, v172
	v_bfe_u32 v158, v156, 16, 1
	v_add3_u32 v156, v156, v158, s52
	v_lshl_add_u64 v[226:227], v[224:225], 0, v[198:199]
	global_store_short_d16_hi v[226:227], v156, off
	v_mul_f32_e32 v156, v26, v172
	v_bfe_u32 v158, v156, 16, 1
	v_add3_u32 v156, v156, v158, s52
	v_lshl_add_u64 v[226:227], v[224:225], 0, v[200:201]
	global_store_short_d16_hi v[226:227], v156, off
	v_mul_f32_e32 v156, v27, v172
	v_bfe_u32 v158, v156, 16, 1
	v_add3_u32 v156, v156, v158, s52
	v_lshl_add_u64 v[226:227], v[224:225], 0, v[202:203]
	global_store_short_d16_hi v[226:227], v156, off
	v_mul_f32_e32 v156, v20, v172
	v_bfe_u32 v158, v156, 16, 1
	v_add3_u32 v156, v156, v158, s52
	global_store_short_d16_hi v[204:205], v156, off offset:64
	v_mul_f32_e32 v156, v21, v172
	v_bfe_u32 v158, v156, 16, 1
	v_add3_u32 v156, v156, v158, s52
	v_lshl_add_u64 v[226:227], v[224:225], 0, v[206:207]
	global_store_short_d16_hi v[226:227], v156, off
	v_mul_f32_e32 v156, v22, v172
	v_bfe_u32 v158, v156, 16, 1
	v_add3_u32 v156, v156, v158, s52
	v_lshl_add_u64 v[226:227], v[224:225], 0, v[208:209]
	global_store_short_d16_hi v[226:227], v156, off
	v_mul_f32_e32 v156, v23, v172
	v_bfe_u32 v158, v156, 16, 1
	v_add3_u32 v156, v156, v158, s52
	v_lshl_add_u64 v[226:227], v[224:225], 0, v[210:211]
	global_store_short_d16_hi v[226:227], v156, off
	v_mul_f32_e32 v156, v16, v172
	v_bfe_u32 v158, v156, 16, 1
	v_add3_u32 v156, v156, v158, s52
	v_lshl_add_u64 v[226:227], v[224:225], 0, v[216:217]
	global_store_short_d16_hi v[226:227], v156, off
	v_mul_f32_e32 v156, v17, v172
	v_bfe_u32 v158, v156, 16, 1
	v_add3_u32 v156, v156, v158, s52
	v_lshl_add_u64 v[226:227], v[224:225], 0, v[218:219]
	global_store_short_d16_hi v[226:227], v156, off
	v_mul_f32_e32 v156, v18, v172
	v_bfe_u32 v158, v156, 16, 1
	v_add3_u32 v156, v156, v158, s52
	v_lshl_add_u64 v[226:227], v[224:225], 0, v[220:221]
	global_store_short_d16_hi v[226:227], v156, off
	v_mul_f32_e32 v156, v19, v172
	v_bfe_u32 v158, v156, 16, 1
	v_add3_u32 v156, v156, v158, s52
	v_lshl_add_u64 v[224:225], v[224:225], 0, v[222:223]
	global_store_short_d16_hi v[224:225], v156, off
	v_mul_f32_e32 v156, v12, v170
	v_bfe_u32 v158, v156, 16, 1
	v_add3_u32 v156, v156, v158, s52
	global_store_short_d16_hi v[188:189], v156, off offset:96
	v_mul_f32_e32 v156, v13, v170
	v_lshl_add_u64 v[186:187], v[186:187], 0, s[38:39]
	v_bfe_u32 v158, v156, 16, 1
	v_add3_u32 v156, v156, v158, s52
	v_lshl_add_u64 v[188:189], v[186:187], 0, v[190:191]
	global_store_short_d16_hi v[188:189], v156, off
	v_mul_f32_e32 v156, v14, v170
	v_bfe_u32 v158, v156, 16, 1
	v_add3_u32 v156, v156, v158, s52
	v_lshl_add_u64 v[188:189], v[186:187], 0, v[192:193]
	global_store_short_d16_hi v[188:189], v156, off
	v_mul_f32_e32 v156, v15, v170
	v_bfe_u32 v158, v156, 16, 1
	v_add3_u32 v156, v156, v158, s52
	v_lshl_add_u64 v[188:189], v[186:187], 0, v[194:195]
	global_store_short_d16_hi v[188:189], v156, off
	v_mul_f32_e32 v156, v8, v170
	v_bfe_u32 v158, v156, 16, 1
	v_add3_u32 v156, v156, v158, s52
	v_lshl_add_u64 v[188:189], v[186:187], 0, v[196:197]
	global_store_short_d16_hi v[188:189], v156, off
	v_mul_f32_e32 v156, v9, v170
	v_bfe_u32 v158, v156, 16, 1
	v_add3_u32 v156, v156, v158, s52
	v_lshl_add_u64 v[188:189], v[186:187], 0, v[198:199]
	global_store_short_d16_hi v[188:189], v156, off
	v_mul_f32_e32 v156, v10, v170
	v_bfe_u32 v158, v156, 16, 1
	v_add3_u32 v156, v156, v158, s52
	v_lshl_add_u64 v[188:189], v[186:187], 0, v[200:201]
	global_store_short_d16_hi v[188:189], v156, off
	v_mul_f32_e32 v156, v11, v170
	v_bfe_u32 v158, v156, 16, 1
	v_add3_u32 v156, v156, v158, s52
	v_lshl_add_u64 v[188:189], v[186:187], 0, v[202:203]
	global_store_short_d16_hi v[188:189], v156, off
	v_mul_f32_e32 v156, v4, v170
	v_bfe_u32 v158, v156, 16, 1
	v_add3_u32 v156, v156, v158, s52
	global_store_short_d16_hi v[204:205], v156, off offset:96
	v_mul_f32_e32 v156, v5, v170
	v_bfe_u32 v158, v156, 16, 1
	v_add3_u32 v156, v156, v158, s52
	v_lshl_add_u64 v[188:189], v[186:187], 0, v[206:207]
	global_store_short_d16_hi v[188:189], v156, off
	v_mul_f32_e32 v156, v6, v170
	v_bfe_u32 v158, v156, 16, 1
	v_add3_u32 v156, v156, v158, s52
	v_lshl_add_u64 v[188:189], v[186:187], 0, v[208:209]
	global_store_short_d16_hi v[188:189], v156, off
	v_mul_f32_e32 v156, v7, v170
	v_bfe_u32 v158, v156, 16, 1
	v_add3_u32 v156, v156, v158, s52
	v_lshl_add_u64 v[188:189], v[186:187], 0, v[210:211]
	global_store_short_d16_hi v[188:189], v156, off
	v_mul_f32_e32 v156, v0, v170
	v_bfe_u32 v158, v156, 16, 1
	v_add3_u32 v156, v156, v158, s52
	v_lshl_add_u64 v[188:189], v[186:187], 0, v[216:217]
	global_store_short_d16_hi v[188:189], v156, off
	v_mul_f32_e32 v156, v1, v170
	v_bfe_u32 v158, v156, 16, 1
	v_add3_u32 v156, v156, v158, s52
	v_lshl_add_u64 v[188:189], v[186:187], 0, v[218:219]
	global_store_short_d16_hi v[188:189], v156, off
	v_mul_f32_e32 v156, v2, v170
	v_bfe_u32 v158, v156, 16, 1
	v_add3_u32 v156, v156, v158, s52
	v_lshl_add_u64 v[188:189], v[186:187], 0, v[220:221]
	global_store_short_d16_hi v[188:189], v156, off
	v_mul_f32_e32 v156, v3, v170
	v_bfe_u32 v158, v156, 16, 1
	v_add3_u32 v156, v156, v158, s52
	v_lshl_add_u64 v[186:187], v[186:187], 0, v[222:223]
	global_store_short_d16_hi v[186:187], v156, off

; __device__ __forceinline__ int crow(int r, int hi) { return (r & 3) + 8 * (r >> 2) + 4 * hi; }
; __device__ __forceinline__ void sb_task(int task, const bf16_t* Q, const bf16_t* Kb, const bf16_t* Vt, bf16_t* MIX, float* ss_sb, int lane, bool do_atomic = true) {
;     const int r32 = lane & 31, hi = lane >> 5;
;     const int qb = task & 255, h = (task >> 8) & 7, b = task >> 11;
;     const size_t rowbase = (size_t)b * SEQ; const int q0 = qb * 32;
;     bf16x8 qf[4];
;     { const bf16_t* qp = Q + (rowbase + q0 + r32) * 512 + h * 64 + hi * 8;
; #pragma unroll
;       for (int ks = 0; ks < 4; ++ks) qf[ks] = *(const bf16x8*)(qp + ks * 16); }
;     f32x16 o0, o1;
; #pragma unroll
;     for (int r = 0; r < 16; ++r) { o0[r] = 0.f; o1[r] = 0.f; }
;     float R = 0.f;
;     const bf16_t* vt = Vt + (size_t)(b * 8 + h) * 64 * SEQ;
;     for (int k0 = q0; k0 >= 0; k0 -= 32) {
;         const bf16_t* kp = Kb + (rowbase + k0 + r32) * 512 + h * 64 + hi * 8;
;         bf16x8 kf[4];
; #pragma unroll
;         for (int ks = 0; ks < 4; ++ks) kf[ks] = *(const bf16x8*)(kp + ks * 16);
;         s16x4 vlo[2][2], vhi[2][2];
; #pragma unroll
;         for (int j = 0; j < 2; ++j)
; #pragma unroll
;             for (int db = 0; db < 2; ++db) { const bf16_t* vp = vt + (size_t)(32 * db + r32) * SEQ + k0 + 16 * j + 4 * hi; vlo[j][db] = *(const s16x4*)vp; vhi[j][db] = *(const s16x4*)(vp + 8); }
;     ...
;             if (diag && crow(r, hi) >= r32) Lv = 0.f;
.LBB0_325:
	s_mov_b64 s[40:41], 0xb800000
	s_or_b64 exec, exec, s[0:1]
	v_readlane_b32 s0, v215, 40
	s_cmpk_lt_i32 s54, 0x1000
	v_readlane_b32 s1, v215, 41
	s_cselect_b64 s[2:3], -1, 0
	s_mul_i32 s0, s0, 0x18000
	s_mov_b32 s1, s97
	v_writelane_b32 v215, s0, 45
	s_and_b64 vcc, exec, s[2:3]
	s_waitcnt lgkmcnt(0)
	s_barrier
	v_writelane_b32 v215, s1, 46
	v_mbcnt_lo_u32_b32 v0, -1, 0
	v_mbcnt_hi_u32_b32 v0, -1, v0
	s_cbranch_vccz .LBB0_367
	v_readlane_b32 s0, v215, 45
	v_readlane_b32 s1, v215, 46
	s_lshl_b64 s[0:1], s[0:1], 2
	v_ashrrev_i32_e32 v1, 5, v0
	s_add_u32 s0, s42, s0
	v_lshlrev_b32_e32 v82, 3, v1
	s_addc_u32 s1, s43, s1
	v_ashrrev_i32_e32 v83, 31, v82
	v_lshlrev_b32_e32 v86, 2, v1
	s_add_u32 s46, s0, 0x10000
	v_lshlrev_b64 v[2:3], 1, v[82:83]
	v_ashrrev_i32_e32 v87, 31, v86
	s_addc_u32 s47, s1, 0
	v_and_b32_e32 v80, 31, v0
	v_lshl_add_u64 v[4:5], s[42:43], 0, v[2:3]
	s_mov_b64 s[0:1], 0x7000000
	v_lshlrev_b64 v[6:7], 2, v[86:87]
	v_lshl_add_u64 v[84:85], v[4:5], 0, s[0:1]
	v_lshlrev_b32_e32 v4, 13, v80
	v_lshl_add_u64 v[8:9], s[42:43], 0, v[6:7]
	s_mov_b64 s[0:1], 0x8000000
	v_lshlrev_b32_e32 v156, 1, v80
	s_add_u32 s88, s42, 0x6000000
	v_lshl_add_u64 v[88:89], v[8:9], 0, s[0:1]
	v_cmp_gt_u32_e64 s[4:5], 32, v0
	v_or_b32_e32 v0, 0x40000, v4
	v_or_b32_e32 v90, 1, v86
	v_or_b32_e32 v92, 2, v86
	v_or_b32_e32 v94, 3, v86
	v_add_u32_e32 v96, 8, v86
	v_add_u32_e32 v98, 11, v86
	v_add_u32_e32 v100, 9, v86
	v_add_u32_e32 v102, 16, v86
	v_add_u32_e32 v104, 10, v86
	v_add_u32_e32 v106, 17, v86
	v_add_u32_e32 v108, 18, v86
	v_add_u32_e32 v110, 19, v86
	v_add_u32_e32 v112, 24, v86
	v_add_u32_e32 v114, 25, v86
	v_add_u32_e32 v116, 26, v86
	v_add_u32_e32 v118, 27, v86
	v_lshl_add_u64 v[8:9], s[42:43], 0, v[156:157]
	v_lshlrev_b32_e32 v156, 14, v80
	s_mov_b64 s[48:49], 0x7000040
	s_addc_u32 s89, s43, 0
	v_mov_b32_e32 v81, v157
	v_cmp_eq_u32_e64 s[0:1], 0, v214
	v_cmp_lt_i32_e64 s[6:7], v86, v80
	v_cmp_lt_i32_e64 s[8:9], v90, v80
	v_cmp_lt_i32_e64 s[10:11], v92, v80
	v_cmp_lt_i32_e64 s[12:13], v94, v80
	v_cmp_lt_i32_e64 s[14:15], v96, v80
	v_cmp_lt_i32_e64 s[16:17], v98, v80
	v_cmp_lt_i32_e64 s[18:19], v102, v80
	v_cmp_lt_i32_e64 s[20:21], v100, v80
	v_cmp_lt_i32_e64 s[22:23], v106, v80
	v_cmp_lt_i32_e64 s[24:25], v104, v80
	v_cmp_lt_i32_e64 s[26:27], v108, v80
	v_cmp_lt_i32_e64 s[28:29], v110, v80
	v_cmp_lt_i32_e64 s[30:31], v112, v80
	v_cmp_lt_i32_e64 s[34:35], v114, v80
	v_cmp_lt_i32_e64 s[36:37], v116, v80
	v_cmp_lt_i32_e64 s[38:39], v118, v80
	v_lshl_add_u64 v[120:121], v[8:9], 0, s[40:41]
	v_cmp_eq_u32_e64 s[40:41], 0, v80
	v_ashrrev_i32_e32 v91, 31, v90
	v_ashrrev_i32_e32 v93, 31, v92
	v_ashrrev_i32_e32 v95, 31, v94
	v_ashrrev_i32_e32 v97, 31, v96
	v_ashrrev_i32_e32 v101, 31, v100
	v_ashrrev_i32_e32 v105, 31, v104
	v_ashrrev_i32_e32 v99, 31, v98
	v_ashrrev_i32_e32 v103, 31, v102
	v_ashrrev_i32_e32 v107, 31, v106
	v_ashrrev_i32_e32 v109, 31, v108
	v_ashrrev_i32_e32 v111, 31, v110
	v_ashrrev_i32_e32 v113, 31, v112
	v_ashrrev_i32_e32 v115, 31, v114
	v_ashrrev_i32_e32 v117, 31, v116
	v_ashrrev_i32_e32 v119, 31, v118
	v_lshl_add_u64 v[122:123], v[156:157], 0, v[6:7]
	s_lshl_b32 s55, s54, 5
	v_lshl_add_u64 v[124:125], v[2:3], 0, s[48:49]
	v_lshlrev_b32_e32 v156, 1, v4
	v_lshlrev_b32_e32 v126, 1, v0
	s_mov_b32 s56, s54
	s_branch .LBB0_328

; __device__ __forceinline__ float ex2(float x) { return __builtin_amdgcn_exp2f(x); }
; __device__ __forceinline__ float lg2(float x) { return __builtin_amdgcn_logf(x); }
; __device__ __forceinline__ int crow(int r, int hi) { return (r & 3) + 8 * (r >> 2) + 4 * hi; }
; __device__ __forceinline__ void sb_task(int task, const bf16_t* Q, const bf16_t* Kb, const bf16_t* Vt, bf16_t* MIX, float* ss_sb, int lane, bool do_atomic = true) {
;     ...
;     for (int k0 = q0; k0 >= 0; k0 -= 32) {
;         const bf16_t* kp = Kb + (rowbase + k0 + r32) * 512 + h * 64 + hi * 8;
;         bf16x8 kf[4];
; #pragma unroll
;         for (int ks = 0; ks < 4; ++ks) kf[ks] = *(const bf16x8*)(kp + ks * 16);
;         s16x4 vlo[2][2], vhi[2][2];
; #pragma unroll
;         for (int j = 0; j < 2; ++j)
; #pragma unroll
;             for (int db = 0; db < 2; ++db) { const bf16_t* vp = vt + (size_t)(32 * db + r32) * SEQ + k0 + 16 * j + 4 * hi; vlo[j][db] = *(const s16x4*)vp; vhi[j][db] = *(const s16x4*)(vp + 8); }
;         f32x16 s;
; #pragma unroll
;         for (int r = 0; r < 16; ++r) s[r] = 0.f;
; #pragma unroll
;         for (int ks = 0; ks < 4; ++ks) s = MFMA32(kf[ks], qf[ks], s);
;         const bool diag = (k0 == q0);
;         float Lr[16];
; #pragma unroll
;         for (int r = 0; r < 16; ++r) {
;             const float z = s[r];
;             float Lv = fminf(-z, 0.f) - lg2(1.f + ex2(-fabsf(z)));
;             if (diag && crow(r, hi) >= r32) Lv = 0.f;
;             Lr[r] = Lv;
;         }
;         float tot[4], oth[4], pr[4];
; #pragma unroll
;         for (int G = 0; G < 4; ++G) { Lr[4 * G + 2] += Lr[4 * G + 3]; Lr[4 * G + 1] += Lr[4 * G + 2]; Lr[4 * G] += Lr[4 * G + 1]; tot[G] = Lr[4 * G]; }
; #pragma unroll
;         for (int G = 0; G < 4; ++G) { oth[G] = xshfl<32>(tot[G]); pr[G] = tot[G] + oth[G]; }
;         float off[4];
;         { const float sp3 = 0.f, sp2 = pr[3], sp1 = sp2 + pr[2], sp0 = sp1 + pr[1];
;           off[3] = sp3 + R; off[2] = sp2 + R; off[1] = sp1 + R; off[0] = sp0 + R;
;           if (hi == 0) { off[0] += oth[0]; off[1] += oth[1]; off[2] += oth[2]; off[3] += oth[3]; }
;           R += sp0 + pr[0]; }
;         float w[16];
; #pragma unroll
;         for (int r = 0; r < 16; ++r) { float wv = ex2(s[r] + Lr[r] + off[r >> 2]); if (diag && crow(r, hi) >= r32) wv = 0.f; w[r] = wv; }
.LBB0_328:
	s_ashr_i32 s60, s56, 11
	s_ashr_i32 s61, s60, 31
	s_lshl_b32 s58, s56, 5
	s_lshl_b64 s[48:49], s[60:61], 13
	s_and_b32 s58, s58, 0x1fe0
	s_or_b32 s90, s48, s58
	v_mov_b32_e32 v1, s49
	v_or_b32_e32 v0, s90, v80
	s_bfe_u32 s57, s56, 0x30008
	v_lshlrev_b64 v[4:5], 10, v[0:1]
	v_or_b32_e32 v0, s48, v80
	s_lshl_b32 s96, s57, 7
	v_or_b32_e32 v0, s58, v0
	s_waitcnt lgkmcnt(0)
	v_lshl_add_u64 v[2:3], v[84:85], 0, s[96:97]
	v_lshlrev_b64 v[0:1], 10, v[0:1]
	v_lshl_add_u64 v[6:7], v[2:3], 0, v[0:1]
	global_load_dwordx4 v[0:3], v[6:7], off
	v_lshl_add_u64 v[4:5], s[88:89], 0, v[4:5]
	v_lshl_add_u64 v[4:5], v[4:5], 0, s[96:97]
	v_lshl_add_u64 v[28:29], v[82:83], 1, v[4:5]
	global_load_dwordx4 v[48:51], v[28:29], off
	global_load_dwordx4 v[16:19], v[6:7], off offset:32
	global_load_dwordx4 v[52:55], v[28:29], off offset:32
	global_load_dwordx4 v[20:23], v[6:7], off offset:64
	global_load_dwordx4 v[56:59], v[28:29], off offset:64
	global_load_dwordx4 v[24:27], v[6:7], off offset:96
	global_load_dwordx4 v[60:63], v[28:29], off offset:96
	s_lshl_b32 s59, s60, 3
	s_or_b32 s60, s59, s57
	s_ashr_i32 s61, s60, 31
	s_lshl_b64 s[60:61], s[60:61], 20
	s_lshl_b32 s96, s58, 1
	v_mov_b32_e32 v127, v157
	s_mov_b32 s91, s49
	s_waitcnt vmcnt(6)
	v_mfma_f32_32x32x16_bf16 v[0:15], v[0:3], v[48:51], 0
	s_waitcnt vmcnt(4)
	v_mfma_f32_32x32x16_bf16 v[0:15], v[16:19], v[52:55], v[0:15]
	v_lshl_add_u64 v[16:17], v[88:89], 0, s[60:61]
	v_lshl_add_u64 v[16:17], v[16:17], 0, s[96:97]
	v_lshl_add_u64 v[18:19], v[16:17], 0, v[156:157]
	v_lshl_add_u64 v[28:29], v[16:17], 0, v[126:127]
	s_waitcnt vmcnt(2)
	v_mfma_f32_32x32x16_bf16 v[0:15], v[20:23], v[56:59], v[0:15]
	global_load_dwordx4 v[20:23], v[18:19], off
	global_load_dwordx4 v[36:39], v[18:19], off offset:32
	global_load_dwordx4 v[16:19], v[28:29], off
	s_nop 0
	global_load_dwordx4 v[32:35], v[28:29], off offset:32
	s_waitcnt vmcnt(4)
	v_mfma_f32_32x32x16_bf16 v[0:15], v[24:27], v[60:63], v[0:15]
	s_nop 11
	v_exp_f32_e64 v25, -|v0|
	v_exp_f32_e64 v30, -|v1|
	v_exp_f32_e64 v31, -|v2|
	v_exp_f32_e64 v40, -|v3|
	v_exp_f32_e64 v43, -|v5|
	v_exp_f32_e64 v45, -|v6|
	v_exp_f32_e64 v47, -|v7|
	v_exp_f32_e64 v67, -|v9|
	v_exp_f32_e64 v69, -|v10|
	v_exp_f32_e64 v41, -|v4|
	v_exp_f32_e64 v65, -|v8|
	v_exp_f32_e64 v71, -|v11|
	v_exp_f32_e64 v73, -|v12|
	v_max_f32_e64 v29, -v4, -v4
	v_max_f32_e64 v66, -v9, -v9
	v_max_f32_e64 v26, -v1, -v1
	v_max_f32_e64 v28, -v3, -v3
	v_max_f32_e64 v42, -v5, -v5
	v_max_f32_e64 v44, -v6, -v6
	v_max_f32_e64 v46, -v7, -v7
	v_max_f32_e64 v68, -v10, -v10
	v_max_f32_e64 v70, -v11, -v11
	v_min_f32_e32 v127, 0, v29
	v_min_f32_e32 v29, 0, v66
	v_add_f32_e32 v25, 1.0, v25
	v_add_f32_e32 v30, 1.0, v30
	v_add_f32_e32 v31, 1.0, v31
	v_add_f32_e32 v40, 1.0, v40
	v_add_f32_e32 v43, 1.0, v43
	v_add_f32_e32 v45, 1.0, v45
	v_add_f32_e32 v47, 1.0, v47
	v_add_f32_e32 v66, 1.0, v67
	v_add_f32_e32 v67, 1.0, v69
	v_min_f32_e32 v77, 0, v26
	v_min_f32_e32 v79, 0, v28
	v_min_f32_e32 v26, 0, v42
	v_min_f32_e32 v28, 0, v44
	v_min_f32_e32 v42, 0, v46
	v_min_f32_e32 v44, 0, v68
	v_min_f32_e32 v46, 0, v70
	v_add_f32_e32 v41, 1.0, v41
	v_add_f32_e32 v65, 1.0, v65
	v_add_f32_e32 v68, 1.0, v71
	v_add_f32_e32 v69, 1.0, v73
	v_log_f32_e32 v25, v25
	v_log_f32_e32 v30, v30
	v_log_f32_e32 v31, v31
	v_log_f32_e32 v70, v40
	v_log_f32_e32 v40, v43
	v_log_f32_e32 v74, v45
	v_log_f32_e32 v43, v47
	v_log_f32_e32 v45, v67
	v_exp_f32_e64 v76, -|v13|
	v_log_f32_e32 v71, v41
	v_log_f32_e32 v41, v65
	v_log_f32_e32 v47, v68
	v_log_f32_e32 v65, v69
	v_max_f32_e64 v24, -v0, -v0
	v_max_f32_e64 v27, -v2, -v2
	v_max_f32_e64 v64, -v8, -v8
	v_max_f32_e64 v72, -v12, -v12
	v_min_f32_e32 v24, 0, v24
	v_min_f32_e32 v78, 0, v27
	v_min_f32_e32 v27, 0, v64
	v_min_f32_e32 v64, 0, v72
	v_sub_f32_e32 v24, v24, v25
	v_sub_f32_e32 v25, v77, v30
	v_sub_f32_e32 v30, v78, v31
	v_sub_f32_e32 v31, v79, v70
	v_sub_f32_e32 v42, v42, v43
	v_sub_f32_e32 v43, v44, v45
	v_sub_f32_e32 v44, v46, v47
	v_sub_f32_e32 v46, v64, v65
	v_cndmask_b32_e64 v65, 0, v31, s[12:13]
	v_cndmask_b32_e64 v31, 0, v43, s[26:27]
	v_add_f32_e32 v43, 1.0, v76
	v_cndmask_b32_e64 v47, 0, v24, s[6:7]
	v_cndmask_b32_e64 v24, 0, v42, s[16:17]
	v_cndmask_b32_e64 v42, 0, v46, s[30:31]
	v_log_f32_e32 v43, v43
	v_exp_f32_e64 v46, -|v14|
	v_cndmask_b32_e64 v45, 0, v44, s[28:29]
	v_max_f32_e64 v44, -v13, -v13
	v_min_f32_e32 v44, 0, v44
	v_sub_f32_e32 v43, v44, v43
	v_add_f32_e32 v44, 1.0, v46
	v_exp_f32_e64 v46, -|v15|
	v_log_f32_e32 v44, v44
	v_log_f32_e32 v75, v66
	v_sub_f32_e32 v66, v127, v71
	v_cndmask_b32_e64 v64, 0, v30, s[10:11]
	v_cndmask_b32_e64 v30, 0, v66, s[14:15]
	v_max_f32_e64 v66, -v14, -v14
	v_add_f32_e32 v46, 1.0, v46
	v_min_f32_e32 v66, 0, v66
	v_log_f32_e32 v46, v46
	v_sub_f32_e32 v44, v66, v44
	v_cndmask_b32_e64 v67, 0, v44, s[36:37]
	v_max_f32_e64 v44, -v15, -v15
	v_min_f32_e32 v44, 0, v44
	v_sub_f32_e32 v44, v44, v46
	v_cndmask_b32_e64 v25, 0, v25, s[8:9]
	v_cndmask_b32_e64 v44, 0, v44, s[38:39]
	v_add_f32_e32 v66, v64, v65
	v_cndmask_b32_e64 v43, 0, v43, s[34:35]
	v_add_f32_e32 v68, v25, v66
	v_add_f32_e32 v46, v67, v44
	v_add_f32_e32 v69, v47, v68
	v_add_f32_e32 v47, v43, v46
	v_pk_add_f32 v[26:27], v[26:27], v[40:41] neg_lo:[0,1] neg_hi:[0,1]
	v_add_f32_e32 v25, v31, v45
	v_add_f32_e32 v64, v42, v47
	v_mov_b32_e32 v31, v69
	v_mov_b32_e32 v42, v69
	v_cndmask_b32_e64 v41, 0, v27, s[18:19]
	v_cndmask_b32_e64 v40, 0, v26, s[20:21]
	v_pk_add_f32 v[26:27], v[28:29], v[74:75] neg_lo:[0,1] neg_hi:[0,1]
	v_permlane32_swap_b32_e32 v31, v42
	v_cndmask_b32_e64 v27, 0, v27, s[22:23]
	v_cndmask_b32_e64 v26, 0, v26, s[24:25]
	v_cndmask_b32_e64 v70, v31, v42, s[0:1]
	v_mov_b32_e32 v31, v64
; __device__ __forceinline__ unsigned cvt_pk_bf16(float lo, float hi) { f32x2 v = {lo, hi}; bf16x2_t b = __builtin_convertvector(v, bf16x2_t); return __builtin_bit_cast(unsigned, b); }
; __device__ __forceinline__ float ex2(float x) { return __builtin_amdgcn_exp2f(x); }
; __device__ __forceinline__ int crow(int r, int hi) { return (r & 3) + 8 * (r >> 2) + 4 * hi; }
; #define MFMA32(a, b, c) __builtin_amdgcn_mfma_f32_32x32x16_bf16((a), (b), (c), 0, 0, 0)
; __device__ __forceinline__ void sb_task(int task, const bf16_t* Q, const bf16_t* Kb, const bf16_t* Vt, bf16_t* MIX, float* ss_sb, int lane, bool do_atomic = true) {
;     ...
;         float tot[4], oth[4], pr[4];
; #pragma unroll
;         for (int G = 0; G < 4; ++G) { Lr[4 * G + 2] += Lr[4 * G + 3]; Lr[4 * G + 1] += Lr[4 * G + 2]; Lr[4 * G] += Lr[4 * G + 1]; tot[G] = Lr[4 * G]; }
; #pragma unroll
;         for (int G = 0; G < 4; ++G) { oth[G] = xshfl<32>(tot[G]); pr[G] = tot[G] + oth[G]; }
;         float off[4];
;         { const float sp3 = 0.f, sp2 = pr[3], sp1 = sp2 + pr[2], sp0 = sp1 + pr[1];
;           off[3] = sp3 + R; off[2] = sp2 + R; off[1] = sp1 + R; off[0] = sp0 + R;
;           if (hi == 0) { off[0] += oth[0]; off[1] += oth[1]; off[2] += oth[2]; off[3] += oth[3]; }
;           R += sp0 + pr[0]; }
;         float w[16];
; #pragma unroll
;         for (int r = 0; r < 16; ++r) { float wv = ex2(s[r] + Lr[r] + off[r >> 2]); if (diag && crow(r, hi) >= r32) wv = 0.f; w[r] = wv; }
;         bf16x8 pa[2];
; #pragma unroll
;         for (int j = 0; j < 2; ++j) { u32x4 p; p.x = cvt_pk_bf16(w[8 * j], w[8 * j + 1]); p.y = cvt_pk_bf16(w[8 * j + 2], w[8 * j + 3]); p.z = cvt_pk_bf16(w[8 * j + 4], w[8 * j + 5]); p.w = cvt_pk_bf16(w[8 * j + 6], w[8 * j + 7]); pa[j] = __builtin_bit_cast(bf16x8, p); }
; #pragma unroll
;         for (int j = 0; j < 2; ++j) {
;             const bf16x8 v0 = (bf16x8){vlo[j][0][0], vlo[j][0][1], vlo[j][0][2], vlo[j][0][3], vhi[j][0][0], vhi[j][0][1], vhi[j][0][2], vhi[j][0][3]};
;             const bf16x8 v1 = (bf16x8){vlo[j][1][0], vlo[j][1][1], vlo[j][1][2], vlo[j][1][3], vhi[j][1][0], vhi[j][1][1], vhi[j][1][2], vhi[j][1][3]};
;             o0 = MFMA32(pa[j], v0, o0); o1 = MFMA32(pa[j], v1, o1);
;         }
;         if (__all(R < -34.f)) break;
	v_mov_b32_e32 v42, v64
	v_pk_add_f32 v[26:27], v[26:27], v[24:25]
	s_nop 0
	v_permlane32_swap_b32_e32 v31, v42
	v_pk_add_f32 v[28:29], v[40:41], v[26:27]
	v_cndmask_b32_e64 v72, v31, v42, s[0:1]
	v_mov_b32_e32 v31, v29
	v_mov_b32_e32 v40, v29
	s_nop 1
	v_permlane32_swap_b32_e32 v31, v40
	v_cndmask_b32_e64 v31, v31, v40, s[0:1]
	v_pk_add_f32 v[40:41], v[30:31], v[28:29]
	v_add_f32_e32 v43, v64, v72
	v_mov_b32_e32 v30, v40
	v_mov_b32_e32 v42, v40
	s_nop 1
	v_permlane32_swap_b32_e32 v30, v42
	v_cndmask_b32_e64 v42, v30, v42, s[0:1]
	v_pk_add_f32 v[74:75], v[40:41], v[42:43]
	v_add_f32_e32 v43, 0, v43
	v_add_f32_e32 v41, v74, v75
	v_add_f32_e32 v67, 0, v75
	v_add_f32_e32 v71, 0, v41
	v_mov_b32_e32 v30, 0
	s_and_saveexec_b64 vcc, s[4:5]
	v_add_f32_e32 v30, 0, v72
	v_add_f32_e32 v43, v43, v31
	v_add_f32_e32 v67, v67, v42
	v_add_f32_e32 v71, v71, v70
	s_or_b64 exec, exec, vcc
	v_add_f32_e32 v0, v0, v69
	v_add_f32_e32 v1, v1, v68
	v_add_f32_e32 v2, v2, v66
	v_add_f32_e32 v3, v3, v65
	v_add_f32_e32 v4, v4, v40
	v_add_f32_e32 v5, v5, v28
	v_add_f32_e32 v6, v6, v26
	v_add_f32_e32 v7, v7, v24
	v_add_f32_e32 v0, v0, v71
	v_add_f32_e32 v1, v1, v71
	v_add_f32_e32 v2, v2, v71
	v_add_f32_e32 v3, v3, v71
	v_add_f32_e32 v4, v4, v67
	v_add_f32_e32 v5, v5, v67
	v_add_f32_e32 v6, v6, v67
	v_add_f32_e32 v7, v7, v67
	v_exp_f32_e32 v0, v0
	v_exp_f32_e32 v1, v1
	v_exp_f32_e32 v2, v2
	v_exp_f32_e32 v3, v3
	v_exp_f32_e32 v4, v4
	v_exp_f32_e32 v5, v5
	v_exp_f32_e32 v6, v6
	v_exp_f32_e32 v7, v7
	v_add_f32_e32 v8, v8, v29
	v_add_f32_e32 v9, v9, v27
	v_add_f32_e32 v10, v10, v25
	v_add_f32_e32 v11, v11, v45
	v_add_f32_e32 v12, v12, v64
	v_add_f32_e32 v13, v13, v47
	v_add_f32_e32 v14, v14, v46
	v_add_f32_e32 v15, v15, v44
	v_cndmask_b32_e64 v0, 0, v0, s[6:7]
	v_cndmask_b32_e64 v1, 0, v1, s[8:9]
	v_cndmask_b32_e64 v2, 0, v2, s[10:11]
	v_cndmask_b32_e64 v3, 0, v3, s[12:13]
	v_cndmask_b32_e64 v4, 0, v4, s[14:15]
	v_cndmask_b32_e64 v5, 0, v5, s[20:21]
	v_cndmask_b32_e64 v6, 0, v6, s[24:25]
	v_cndmask_b32_e64 v7, 0, v7, s[16:17]
	v_add_f32_e32 v8, v8, v43
	v_add_f32_e32 v9, v9, v43
	v_add_f32_e32 v10, v10, v43
	v_add_f32_e32 v11, v11, v43
	v_add_f32_e32 v12, v12, v30
	v_add_f32_e32 v13, v13, v30
	v_add_f32_e32 v14, v14, v30
	v_add_f32_e32 v15, v15, v30
	v_exp_f32_e32 v8, v8
	v_exp_f32_e32 v9, v9
	v_exp_f32_e32 v10, v10
	v_exp_f32_e32 v11, v11
	v_exp_f32_e32 v12, v12
	v_exp_f32_e32 v13, v13
	v_exp_f32_e32 v14, v14
	v_exp_f32_e32 v15, v15
	v_cvt_pk_bf16_f32 v24, v0, v1
	v_cvt_pk_bf16_f32 v25, v2, v3
	v_cvt_pk_bf16_f32 v26, v4, v5
	v_cvt_pk_bf16_f32 v27, v6, v7
	v_add_f32_e32 v31, v69, v70
	v_cndmask_b32_e64 v8, 0, v8, s[18:19]
	v_cndmask_b32_e64 v9, 0, v9, s[22:23]
	v_cndmask_b32_e64 v10, 0, v10, s[26:27]
	v_cndmask_b32_e64 v11, 0, v11, s[28:29]
	v_cndmask_b32_e64 v12, 0, v12, s[30:31]
	v_cndmask_b32_e64 v13, 0, v13, s[34:35]
	v_cndmask_b32_e64 v14, 0, v14, s[36:37]
	v_cndmask_b32_e64 v15, 0, v15, s[38:39]
	v_add_f32_e32 v41, v31, v41
	v_cvt_pk_bf16_f32 v42, v8, v9
	v_cvt_pk_bf16_f32 v43, v10, v11
	v_cvt_pk_bf16_f32 v44, v12, v13
	v_cvt_pk_bf16_f32 v45, v14, v15
	s_waitcnt vmcnt(3)
	v_mfma_f32_32x32x16_bf16 v[0:15], v[24:27], v[20:23], 0
	v_cmp_gt_f32_e32 vcc, s87, v41
	s_cmp_eq_u64 vcc, exec
	s_cselect_b64 s[60:61], -1, 0
	s_cmp_eq_u32 s58, 0
	s_cselect_b64 s[62:63], -1, 0
	s_or_b64 s[60:61], s[62:63], s[60:61]
	s_and_b64 vcc, exec, s[60:61]
	s_waitcnt vmcnt(1)
	v_mfma_f32_32x32x16_bf16 v[16:31], v[24:27], v[16:19], 0
	v_mfma_f32_32x32x16_bf16 v[0:15], v[42:45], v[36:39], v[0:15]
	s_waitcnt vmcnt(0)
	v_mfma_f32_32x32x16_bf16 v[16:31], v[42:45], v[32:35], v[16:31]
	s_cbranch_vccnz .LBB0_335
	s_lshr_b32 s60, s56, 8
	s_and_b32 vcc_lo, s60, 7
	s_and_b32 s60, s55, 0x1fe0
	s_lshl_b32 s62, vcc_lo, 7
	s_add_i32 vcc_lo, s59, vcc_lo
	s_sub_i32 s96, s60, 32
	s_ashr_i32 vcc_hi, vcc_lo, 31
	s_lshl_b64 s[60:61], s[96:97], 1
	s_lshl_b64 vcc, vcc, 20
	s_add_u32 s60, s60, vcc_lo
	s_addc_u32 s61, s61, vcc_hi
	s_add_u32 s48, s96, s48
	s_addc_u32 s49, 0, s49
	v_lshl_add_u64 v[32:33], s[48:49], 0, v[80:81]
	v_lshlrev_b64 v[32:33], 10, v[32:33]
	s_mov_b32 s63, s97
	v_lshl_add_u64 v[32:33], v[124:125], 0, v[32:33]
	v_add_f32_e32 v127, 0, v41
	v_lshl_add_u64 v[128:129], s[60:61], 0, v[122:123]
	v_lshl_add_u64 v[130:131], v[32:33], 0, s[62:63]
	s_branch .LBB0_333
.LBB0_332:
	s_or_b64 exec, exec, s[48:49]
	v_add_f32_e32 v32, v32, v153
	v_add_f32_e32 v33, v33, v166
	v_add_f32_e32 v34, v34, v155
	v_add_f32_e32 v35, v35, v152
	v_add_f32_e32 v36, v36, v148
	v_add_f32_e32 v37, v37, v167
	v_add_f32_e32 v32, v32, v149
	v_add_f32_e32 v33, v33, v149
	v_add_f32_e32 v34, v34, v149
	v_add_f32_e32 v35, v35, v149
	v_add_f32_e32 v36, v36, v146
	v_add_f32_e32 v37, v37, v146
	v_exp_f32_e32 v32, v32
	v_exp_f32_e32 v33, v33
	v_exp_f32_e32 v34, v34
	v_exp_f32_e32 v35, v35
	v_exp_f32_e32 v36, v36
	v_exp_f32_e32 v37, v37
	v_add_f32_e32 v38, v38, v154
	v_add_f32_e32 v39, v39, v133
	v_add_f32_e32 v38, v38, v146
	v_add_f32_e32 v39, v39, v146
	v_exp_f32_e32 v38, v38
	v_exp_f32_e32 v39, v39
	v_cvt_pk_bf16_f32 v32, v32, v33
	v_cvt_pk_bf16_f32 v33, v34, v35
	v_cvt_pk_bf16_f32 v34, v36, v37
	v_add_f32_e32 v36, v45, v138
	v_add_f32_e32 v36, v36, v144
	v_add_f32_e32 v44, v44, v140
	v_cvt_pk_bf16_f32 v35, v38, v39
	v_exp_f32_e32 v39, v36
	v_add_f32_e32 v36, v46, v136
	v_add_f32_e32 v44, v44, v144
	v_add_f32_e32 v36, v36, v144
	v_add_f32_e32 v40, v40, v141
	v_add_f32_e32 v41, v41, v139
	v_add_f32_e32 v42, v42, v137
	v_add_f32_e32 v43, v43, v135
	v_exp_f32_e32 v38, v44
	v_exp_f32_e32 v44, v36
	v_add_f32_e32 v36, v47, v147
	v_add_f32_e32 v40, v40, v145
	v_add_f32_e32 v41, v41, v145
	v_add_f32_e32 v42, v42, v145
	v_add_f32_e32 v43, v43, v145
	v_add_f32_e32 v36, v36, v144
	v_exp_f32_e32 v40, v40
	v_exp_f32_e32 v41, v41
	v_exp_f32_e32 v42, v42
	v_exp_f32_e32 v43, v43
	v_exp_f32_e32 v45, v36
	s_waitcnt vmcnt(3)
	v_mfma_f32_32x32x16_bf16 v[0:15], v[32:35], v[76:79], v[0:15]
	v_cvt_pk_bf16_f32 v36, v40, v41
	v_cvt_pk_bf16_f32 v37, v42, v43
	v_cvt_pk_bf16_f32 v38, v38, v39
	v_cvt_pk_bf16_f32 v39, v44, v45
	s_waitcnt vmcnt(2)
	v_mfma_f32_32x32x16_bf16 v[16:31], v[32:35], v[72:75], v[16:31]
	v_add_f32_e32 v32, v153, v132
	v_add_f32_e32 v32, v32, v134
	v_add_f32_e32 v127, v127, v32
	v_cmp_gt_f32_e32 vcc, s87, v127
	s_cmp_lg_u64 vcc, exec
	s_cselect_b64 s[48:49], -1, 0
	s_cmp_gt_u32 s58, 63
	s_waitcnt vmcnt(1)
	v_mfma_f32_32x32x16_bf16 v[0:15], v[36:39], v[68:71], v[0:15]
	s_cselect_b64 s[60:61], -1, 0
	s_and_b64 s[48:49], s[48:49], s[60:61]
	s_movk_i32 s60, 0xffc0
	s_mov_b32 s61, -1
	v_lshl_add_u64 v[128:129], v[128:129], 0, s[60:61]
	s_movk_i32 s60, 0x8000
	s_mov_b32 s61, -1
	s_waitcnt vmcnt(0)
	v_mfma_f32_32x32x16_bf16 v[16:31], v[36:39], v[64:67], v[16:31]
	v_lshl_add_u64 v[130:131], v[130:131], 0, s[60:61]
	s_sub_i32 s58, s58, 32
	s_and_b64 vcc, exec, s[48:49]
	s_cbranch_vccz .LBB0_335
; __device__ __forceinline__ float ex2(float x) { return __builtin_amdgcn_exp2f(x); }
; __device__ __forceinline__ float lg2(float x) { return __builtin_amdgcn_logf(x); }
; __device__ __forceinline__ int crow(int r, int hi) { return (r & 3) + 8 * (r >> 2) + 4 * hi; }
; #define MFMA32(a, b, c) __builtin_amdgcn_mfma_f32_32x32x16_bf16((a), (b), (c), 0, 0, 0)
; __device__ __forceinline__ void sb_task(int task, const bf16_t* Q, const bf16_t* Kb, const bf16_t* Vt, bf16_t* MIX, float* ss_sb, int lane, bool do_atomic = true) {
;     ...
;     for (int k0 = q0; k0 >= 0; k0 -= 32) {
;         const bf16_t* kp = Kb + (rowbase + k0 + r32) * 512 + h * 64 + hi * 8;
;         bf16x8 kf[4];
; #pragma unroll
;         for (int ks = 0; ks < 4; ++ks) kf[ks] = *(const bf16x8*)(kp + ks * 16);
;         s16x4 vlo[2][2], vhi[2][2];
; #pragma unroll
;         for (int j = 0; j < 2; ++j)
; #pragma unroll
;             for (int db = 0; db < 2; ++db) { const bf16_t* vp = vt + (size_t)(32 * db + r32) * SEQ + k0 + 16 * j + 4 * hi; vlo[j][db] = *(const s16x4*)vp; vhi[j][db] = *(const s16x4*)(vp + 8); }
;         f32x16 s;
; #pragma unroll
;         for (int r = 0; r < 16; ++r) s[r] = 0.f;
; #pragma unroll
;         for (int ks = 0; ks < 4; ++ks) s = MFMA32(kf[ks], qf[ks], s);
;         const bool diag = (k0 == q0);
;         float Lr[16];
; #pragma unroll
;         for (int r = 0; r < 16; ++r) {
;             const float z = s[r];
;             float Lv = fminf(-z, 0.f) - lg2(1.f + ex2(-fabsf(z)));
;             if (diag && crow(r, hi) >= r32) Lv = 0.f;
;             Lr[r] = Lv;
;         }
;         float tot[4], oth[4], pr[4];
; #pragma unroll
;         for (int G = 0; G < 4; ++G) { Lr[4 * G + 2] += Lr[4 * G + 3]; Lr[4 * G + 1] += Lr[4 * G + 2]; Lr[4 * G] += Lr[4 * G + 1]; tot[G] = Lr[4 * G]; }
; #pragma unroll
;         for (int G = 0; G < 4; ++G) { oth[G] = xshfl<32>(tot[G]); pr[G] = tot[G] + oth[G]; }
;         float off[4];
;         { const float sp3 = 0.f, sp2 = pr[3], sp1 = sp2 + pr[2], sp0 = sp1 + pr[1];
;           off[3] = sp3 + R; off[2] = sp2 + R; off[1] = sp1 + R; off[0] = sp0 + R;
;           if (hi == 0) { off[0] += oth[0]; off[1] += oth[1]; off[2] += oth[2]; off[3] += oth[3]; }
;           R += sp0 + pr[0]; }
.LBB0_333:
	v_lshl_add_u64 v[36:37], s[42:43], 0, v[130:131]
	global_load_dwordx4 v[32:35], v[36:37], off offset:-64
	global_load_dwordx4 v[132:135], v[36:37], off offset:-32
	global_load_dwordx4 v[136:139], v[36:37], off
	global_load_dwordx4 v[140:143], v[36:37], off offset:32
	v_lshl_add_u64 v[36:37], s[42:43], 0, v[128:129]
	v_add_co_u32_e32 v38, vcc, 0x8000000, v36
	s_nop 1
	v_addc_co_u32_e32 v39, vcc, 0, v37, vcc
	v_add_co_u32_e32 v36, vcc, 0x8080000, v36
	global_load_dwordx4 v[76:79], v[38:39], off
	v_addc_co_u32_e32 v37, vcc, 0, v37, vcc
	global_load_dwordx4 v[72:75], v[36:37], off
	global_load_dwordx4 v[68:71], v[38:39], off offset:32
	global_load_dwordx4 v[64:67], v[36:37], off offset:32
	s_waitcnt vmcnt(7)
	v_mfma_f32_32x32x16_bf16 v[32:47], v[32:35], v[48:51], 0
	s_waitcnt vmcnt(6)
	v_mfma_f32_32x32x16_bf16 v[32:47], v[132:135], v[52:55], v[32:47]
	s_waitcnt vmcnt(5)
	v_mfma_f32_32x32x16_bf16 v[32:47], v[136:139], v[56:59], v[32:47]
	s_waitcnt vmcnt(4)
	v_mfma_f32_32x32x16_bf16 v[32:47], v[140:143], v[60:63], v[32:47]
	s_nop 11
	v_exp_f32_e64 v133, -|v32|
	v_max_f32_e64 v132, -v32, -v32
	v_min_f32_e32 v132, 0, v132
	v_exp_f32_e64 v135, -|v39|
	v_add_f32_e32 v133, 1.0, v133
	v_log_f32_e32 v133, v133
	v_exp_f32_e64 v147, -|v46|
	v_add_f32_e32 v135, 1.0, v135
	v_log_f32_e32 v137, v135
	v_sub_f32_e32 v134, v132, v133
	v_exp_f32_e64 v133, -|v33|
	v_max_f32_e64 v132, -v33, -v33
	v_min_f32_e32 v132, 0, v132
	v_max_f32_e64 v135, -v40, -v40
	v_add_f32_e32 v133, 1.0, v133
	v_log_f32_e32 v133, v133
	v_exp_f32_e64 v149, -|v47|
	v_exp_f32_e64 v138, -|v44|
	v_exp_f32_e64 v142, -|v45|
	v_sub_f32_e32 v144, v132, v133
	v_exp_f32_e64 v133, -|v34|
	v_max_f32_e64 v132, -v34, -v34
	v_min_f32_e32 v132, 0, v132
	v_add_f32_e32 v147, 1.0, v147
	v_add_f32_e32 v133, 1.0, v133
	v_log_f32_e32 v133, v133
	v_add_f32_e32 v149, 1.0, v149
	v_log_f32_e32 v148, v147
	v_log_f32_e32 v149, v149
	v_sub_f32_e32 v150, v132, v133
	v_exp_f32_e64 v133, -|v35|
	v_max_f32_e64 v132, -v35, -v35
	v_min_f32_e32 v132, 0, v132
	v_max_f32_e64 v146, -v46, -v46
	v_add_f32_e32 v133, 1.0, v133
	v_log_f32_e32 v133, v133
	v_max_f32_e64 v147, -v47, -v47
	v_add_f32_e32 v138, 1.0, v138
	v_add_f32_e32 v142, 1.0, v142
	v_sub_f32_e32 v152, v132, v133
	v_exp_f32_e64 v133, -|v36|
	v_max_f32_e64 v132, -v36, -v36
	v_min_f32_e32 v132, 0, v132
	v_add_f32_e32 v155, v150, v152
	v_add_f32_e32 v133, 1.0, v133
	v_log_f32_e32 v133, v133
	v_add_f32_e32 v166, v144, v155
	v_add_f32_e32 v153, v134, v166
	v_min_f32_e32 v146, 0, v146
	v_sub_f32_e32 v151, v132, v133
	v_exp_f32_e64 v133, -|v37|
	v_max_f32_e64 v132, -v37, -v37
	v_min_f32_e32 v132, 0, v132
	v_min_f32_e32 v147, 0, v147
	v_add_f32_e32 v133, 1.0, v133
	v_log_f32_e32 v133, v133
	v_mov_b32_e32 v134, v153
	v_log_f32_e32 v138, v138
	v_log_f32_e32 v142, v142
	v_sub_f32_e32 v158, v132, v133
	v_exp_f32_e64 v133, -|v38|
	v_max_f32_e64 v132, -v38, -v38
	v_min_f32_e32 v132, 0, v132
	v_pk_add_f32 v[146:147], v[146:147], v[148:149] neg_lo:[0,1] neg_hi:[0,1]
	v_add_f32_e32 v133, 1.0, v133
	v_log_f32_e32 v136, v133
	v_max_f32_e64 v133, -v39, -v39
	v_min_f32_e32 v133, 0, v133
	v_max_f32_e64 v140, -v45, -v45
	v_pk_add_f32 v[132:133], v[132:133], v[136:137] neg_lo:[0,1] neg_hi:[0,1]
	v_min_f32_e32 v137, 0, v135
	v_exp_f32_e64 v135, -|v40|
	v_exp_f32_e64 v136, -|v42|
	v_add_f32_e32 v154, v132, v133
	v_add_f32_e32 v167, v158, v154
	v_add_f32_e32 v135, 1.0, v135
	v_log_f32_e32 v139, v135
	v_max_f32_e64 v135, -v41, -v41
	v_min_f32_e32 v141, 0, v135
	v_exp_f32_e64 v135, -|v41|
	v_add_f32_e32 v136, 1.0, v136
	v_log_f32_e32 v136, v136
	v_mov_b32_e32 v132, v153
	v_add_f32_e32 v135, 1.0, v135
	v_log_f32_e32 v143, v135
	v_max_f32_e64 v135, -v42, -v42
	v_min_f32_e32 v135, 0, v135
	v_sub_f32_e32 v145, v135, v136
	v_exp_f32_e64 v136, -|v43|
	v_max_f32_e64 v135, -v43, -v43
	v_add_f32_e32 v148, v151, v167
	v_permlane32_swap_b32_e32 v132, v134
	v_add_f32_e32 v136, 1.0, v136
	v_log_f32_e32 v136, v136
	v_min_f32_e32 v135, 0, v135
	v_cndmask_b32_e64 v132, v132, v134, s[0:1]
	v_mov_b32_e32 v134, v148
	v_mov_b32_e32 v144, v148
	v_sub_f32_e32 v135, v135, v136
	v_max_f32_e64 v136, -v44, -v44
	v_permlane32_swap_b32_e32 v134, v144
	v_min_f32_e32 v136, 0, v136
	v_min_f32_e32 v140, 0, v140
	v_cndmask_b32_e64 v150, v134, v144, s[0:1]
	v_mov_b32_e32 v144, v146
	v_mov_b32_e32 v134, v147
	v_pk_add_f32 v[168:169], v[136:137], v[138:139] neg_lo:[0,1] neg_hi:[0,1]
	v_pk_add_f32 v[138:139], v[140:141], v[142:143] neg_lo:[0,1] neg_hi:[0,1]
	v_pk_add_f32 v[136:137], v[144:145], v[134:135]
	s_nop 0
	v_pk_add_f32 v[138:139], v[138:139], v[136:137]
	s_nop 0
	v_pk_add_f32 v[140:141], v[168:169], v[138:139]
	s_nop 0
	v_mov_b32_e32 v134, v141
	v_mov_b32_e32 v142, v141
	v_mov_b32_e32 v144, v140
	v_mov_b32_e32 v145, v140
	v_permlane32_swap_b32_e32 v134, v142
	s_nop 0
	v_permlane32_swap_b32_e32 v144, v145
	v_cndmask_b32_e64 v143, v134, v142, s[0:1]
	v_cndmask_b32_e64 v142, v144, v145, s[0:1]
	v_pk_add_f32 v[168:169], v[140:141], v[142:143]
	v_add_f32_e32 v144, 0, v127
	v_mov_b32_e32 v149, v168
	v_mov_b32_e32 v151, v169
	v_pk_add_f32 v[170:171], v[148:149], v[150:151]
	v_add_f32_e32 v145, v127, v168
	v_add_f32_e32 v134, v170, v171
	v_add_f32_e32 v146, v127, v171
	v_add_f32_e32 v149, v127, v134
	s_and_saveexec_b64 s[48:49], s[4:5]
	s_cbranch_execz .LBB0_332
	v_add_f32_e32 v144, v144, v142
	v_add_f32_e32 v145, v145, v143
	v_add_f32_e32 v146, v146, v150
	v_add_f32_e32 v149, v149, v132
	s_branch .LBB0_332
